# attention both units: K, K-rope and V tiles staged by LDS-DMA (no VGPR round trip, no ds_write staging); V read with ds_read_b64_tr_b16
# speedup vs baseline: 1.0109x; 1.0029x over previous
.LBB0_574:
	s_or_b64 exec, exec, s[10:11]
	v_lshl_add_u64 v[0:1], s[38:39], 0, v[122:123]
	s_lshl_b32 s10, s28, 6
	v_lshlrev_b64 v[0:1], 11, v[0:1]
	v_lshl_add_u64 v[0:1], s[8:9], 0, v[0:1]
	s_lshl_b32 s46, s10, 1
	s_mov_b32 s47, s39
	v_lshl_add_u64 v[0:1], v[0:1], 0, s[46:47]
	v_mov_b32_e32 v167, v121
	v_lshl_add_u64 v[180:181], v[0:1], 0, v[166:167]
	v_and_b32_e32 v237, 16, v191
	v_lshlrev_b32_e32 v237, 2, v237
	v_xor_b32_e32 v234, v237, v180
	v_mov_b32_e32 v235, v181
	global_load_dwordx4 v[112:115], v[234:235], off offset:1024
	s_waitcnt vmcnt(0)
	ds_write_b128 v119, v[104:107]
	s_and_saveexec_b64 s[10:11], s[4:5]
	ds_write_b128 v119, v[108:111] offset:8192
	s_or_b64 exec, exec, s[10:11]
	s_lshl_b32 s10, s53, 11
	s_and_b32 s11, s60, 7
	s_and_b32 s10, s10, 0x3800000
	s_lshl_b32 s11, s11, 7
	s_or_b32 s10, s10, s11
	s_mov_b32 s11, s39
	v_lshl_add_u64 v[170:171], v[160:161], 0, s[10:11]
	s_lshl_b32 s28, s53, 6
	v_lshl_add_u64 v[174:175], v[164:165], 0, s[10:11]
	s_add_i32 s10, s62, 0x100
	s_and_b32 s28, s28, 0x1c0000
	s_mov_b32 s29, s39
	s_ashr_i32 s47, s10, 6
	v_lshl_add_u64 v[172:173], v[162:163], 0, s[28:29]
	s_cmp_lt_i32 s47, 1
	ds_write_b128 v119, v[112:115] offset:24576
	s_waitcnt lgkmcnt(0)
	s_barrier
	s_cbranch_scc1 .LBB0_601
	v_mov_b32_e32 v14, v121
	v_mov_b32_e32 v15, v121
	v_mov_b32_e32 v0, v121
	v_mov_b32_e32 v1, v121
	v_mov_b32_e32 v2, v121
	v_mov_b32_e32 v3, v121
	v_mov_b32_e32 v4, v121
	v_mov_b32_e32 v5, v121
	v_mov_b32_e32 v6, v121
	v_mov_b32_e32 v7, v121
	v_mov_b32_e32 v8, v121
	v_mov_b32_e32 v9, v121
	v_mov_b32_e32 v10, v121
	v_mov_b32_e32 v11, v121
	v_mov_b32_e32 v12, v121
	v_mov_b32_e32 v13, v121
	v_mov_b32_e32 v141, 0
	v_mov_b64_e32 v[30:31], v[14:15]
	s_or_b32 s49, s63, 31
	s_sub_i32 s64, 0, s47
	s_mov_b32 s65, 1
	s_mov_b32 s66, 63
	v_mov_b64_e32 v[184:185], v[174:175]
	v_mov_b64_e32 v[186:187], v[172:173]
	v_mov_b64_e32 v[188:189], v[170:171]
	v_xor_b32_e32 v188, v237, v188
	v_bfe_u32 v232, v191, 2, 2
	v_bfe_u32 v233, v191, 5, 1
	v_lshl_add_u32 v233, v233, 2, v232
	v_lshlrev_b32_e32 v238, 7, v233
	v_bfe_u32 v233, v191, 4, 1
	v_bfe_u32 v234, v191, 1, 1
	v_lshl_or_b32 v233, v233, 1, v234
	v_lshrrev_b32_e32 v232, 1, v232
	v_lshlrev_b32_e32 v232, 2, v232
	v_xor_b32_e32 v233, v233, v232
	v_lshl_add_u32 v238, v233, 4, v238
	v_and_b32_e32 v232, 1, v191
	v_lshl_add_u32 v238, v232, 3, v238
	v_xor_b32_e32 v239, 64, v238
	v_readfirstlane_b32 s99, v119
	v_mov_b64_e32 v[28:29], v[12:13]
	v_mov_b64_e32 v[26:27], v[10:11]
	v_mov_b64_e32 v[24:25], v[8:9]
	v_mov_b64_e32 v[22:23], v[6:7]
	v_mov_b64_e32 v[20:21], v[4:5]
	v_mov_b64_e32 v[18:19], v[2:3]
	v_mov_b64_e32 v[16:17], v[0:1]
	v_mov_b32_e32 v139, 0
	v_mov_b32_e32 v32, 0
	v_mov_b32_e32 v33, v141
	v_mov_b32_e32 v34, v141
	v_mov_b32_e32 v35, v141
	v_mov_b32_e32 v36, v141
	v_mov_b32_e32 v37, v141
	v_mov_b32_e32 v38, v141
	v_mov_b32_e32 v39, v141
	v_mov_b32_e32 v40, v141
	v_mov_b32_e32 v41, v141
	v_mov_b32_e32 v42, v141
	v_mov_b32_e32 v43, v141
	v_mov_b32_e32 v44, v141
	v_mov_b32_e32 v45, v141
	v_mov_b32_e32 v46, v141
	v_mov_b32_e32 v47, v141
	s_branch .LBB0_580
.LBB0_578:
	s_waitcnt vmcnt(0)
.LBB0_579:
	s_add_i32 s65, s65, 1
	s_add_i32 s66, s66, 64
	s_add_i32 s10, s64, s65
	v_lshl_add_u64 v[188:189], v[188:189], 0, s[40:41]
	v_lshl_add_u64 v[186:187], v[186:187], 0, s[42:43]
	s_cmp_eq_u32 s10, 1
	v_lshl_add_u64 v[184:185], v[184:185], 0, s[40:41]
	s_waitcnt lgkmcnt(0)
	s_barrier
	s_cbranch_scc1 .LBB0_602
.LBB0_580:
	s_cmp_lt_i32 s65, s47
	s_cselect_b64 s[50:51], -1, 0
	s_cmp_ge_i32 s65, s47
	s_cbranch_scc1 .LBB0_584
	s_and_b32 s10, s65, 1
	s_mul_i32 s11, s10, 0x3000
	s_add_i32 s11, s11, s99
	s_mov_b32 m0, s11
	s_nop 0
	global_load_lds_dwordx4 v[184:185], off
	s_cmp_lg_u64 s[4:5], 0
	s_cbranch_scc0 .LBB0_583
	s_add_i32 m0, s11, 0x2000
	s_nop 0
	global_load_lds_dwordx4 v[186:187], off
.LBB0_583:
	s_mulk_i32 s10, 0x2200
	s_add_i32 s10, s10, s99
	s_add_i32 m0, s10, 0x6000
	s_nop 0
	global_load_lds_dwordx4 v[188:189], off

.LBB0_596:
	v_exp_f32_e32 v192, v64
	v_exp_f32_e32 v193, v65
	v_exp_f32_e32 v196, v48
	v_exp_f32_e32 v197, v49
	v_exp_f32_e32 v194, v66
	v_exp_f32_e32 v195, v67
	v_exp_f32_e32 v198, v50
	v_exp_f32_e32 v199, v51
	v_exp_f32_e32 v200, v68
	v_exp_f32_e32 v201, v69
	v_pk_add_f32 v[48:49], v[196:197], v[192:193]
	v_exp_f32_e32 v202, v52
	v_exp_f32_e32 v203, v53
	v_pk_add_f32 v[48:49], v[194:195], v[48:49]
	v_exp_f32_e32 v204, v70
	v_exp_f32_e32 v205, v71
	v_pk_add_f32 v[48:49], v[198:199], v[48:49]
	v_exp_f32_e32 v206, v54
	v_exp_f32_e32 v207, v55
	v_pk_add_f32 v[48:49], v[200:201], v[48:49]
	v_exp_f32_e32 v208, v72
	v_exp_f32_e32 v209, v73
	v_pk_add_f32 v[48:49], v[202:203], v[48:49]
	v_exp_f32_e32 v210, v56
	v_exp_f32_e32 v211, v57
	v_pk_add_f32 v[48:49], v[204:205], v[48:49]
	v_exp_f32_e32 v212, v74
	v_exp_f32_e32 v213, v75
	v_pk_add_f32 v[48:49], v[206:207], v[48:49]
	v_exp_f32_e32 v214, v58
	v_exp_f32_e32 v215, v59
	v_pk_add_f32 v[48:49], v[208:209], v[48:49]
	v_exp_f32_e32 v216, v76
	v_exp_f32_e32 v217, v77
	v_pk_add_f32 v[48:49], v[210:211], v[48:49]
	v_exp_f32_e32 v218, v60
	v_exp_f32_e32 v219, v61
	v_pk_add_f32 v[48:49], v[212:213], v[48:49]
	v_exp_f32_e32 v220, v78
	v_exp_f32_e32 v221, v79
	v_pk_add_f32 v[48:49], v[214:215], v[48:49]
	v_exp_f32_e32 v222, v62
	v_exp_f32_e32 v223, v63
	v_pk_add_f32 v[48:49], v[216:217], v[48:49]
	s_mul_i32 s10, s67, 0x2200
	v_pk_add_f32 v[48:49], v[218:219], v[48:49]
	v_add_u32_e32 v232, s10, v238
	v_pk_add_f32 v[48:49], v[220:221], v[48:49]
	v_add_u32_e32 v233, s10, v239
	v_pk_add_f32 v[48:49], v[222:223], v[48:49]
	v_pk_add_f32 v[48:49], v[48:49], v[48:49] op_sel:[0,1] op_sel_hi:[1,0]
	v_cvt_pk_bf16_f32 v192, v192, v193
	v_mov_b32_e32 v49, v48
	s_nop 1
	v_permlane32_swap_b32_e32 v48, v49
	v_add_f32_e32 v143, v48, v49
	ds_read_b64_tr_b16 v[48:49], v232 offset:24576
	ds_read_b64_tr_b16 v[50:51], v232 offset:25600
	ds_read_b64_tr_b16 v[52:53], v232 offset:26624
	ds_read_b64_tr_b16 v[54:55], v232 offset:27648
	ds_read_b64_tr_b16 v[56:57], v233 offset:24576
	ds_read_b64_tr_b16 v[58:59], v233 offset:25600
	ds_read_b64_tr_b16 v[60:61], v233 offset:26624
	ds_read_b64_tr_b16 v[62:63], v233 offset:27648
	ds_read_b64_tr_b16 v[64:65], v232 offset:28672
	ds_read_b64_tr_b16 v[66:67], v232 offset:29696
	ds_read_b64_tr_b16 v[68:69], v233 offset:28672
	ds_read_b64_tr_b16 v[70:71], v233 offset:29696
	ds_read_b64_tr_b16 v[72:73], v232 offset:30720
	ds_read_b64_tr_b16 v[74:75], v232 offset:31744
	ds_read_b64_tr_b16 v[76:77], v233 offset:30720
	ds_read_b64_tr_b16 v[78:79], v233 offset:31744
	v_cvt_pk_bf16_f32 v193, v194, v195
	v_cvt_pk_bf16_f32 v194, v200, v201
	v_cvt_pk_bf16_f32 v195, v204, v205
	v_cvt_pk_bf16_f32 v196, v196, v197
	v_cvt_pk_bf16_f32 v197, v198, v199
	v_cvt_pk_bf16_f32 v198, v202, v203
	v_cvt_pk_bf16_f32 v199, v206, v207
	v_cvt_pk_bf16_f32 v200, v208, v209
	v_cvt_pk_bf16_f32 v201, v212, v213
	v_cvt_pk_bf16_f32 v202, v216, v217
	v_cvt_pk_bf16_f32 v203, v220, v221
	v_cvt_pk_bf16_f32 v204, v210, v211
	v_cvt_pk_bf16_f32 v205, v214, v215
	v_cvt_pk_bf16_f32 v206, v218, v219
	v_cvt_pk_bf16_f32 v207, v222, v223
	s_setprio 1
	s_waitcnt lgkmcnt(14)
	v_mfma_f32_32x32x16_bf16 v[0:15], v[192:195], v[48:51], v[0:15]
	v_add_f32_e32 v139, v139, v143
	s_waitcnt lgkmcnt(10)
	v_mfma_f32_32x32x16_bf16 v[16:31], v[192:195], v[56:59], v[16:31]
	v_mfma_f32_32x32x16_bf16 v[0:15], v[200:203], v[52:55], v[0:15]
	s_waitcnt lgkmcnt(8)
	v_mfma_f32_32x32x16_bf16 v[16:31], v[200:203], v[60:63], v[16:31]
	s_waitcnt lgkmcnt(6)
	v_mfma_f32_32x32x16_bf16 v[0:15], v[196:199], v[64:67], v[0:15]
	s_waitcnt lgkmcnt(4)
	v_mfma_f32_32x32x16_bf16 v[16:31], v[196:199], v[68:71], v[16:31]
	s_waitcnt lgkmcnt(2)
	v_mfma_f32_32x32x16_bf16 v[0:15], v[204:207], v[72:75], v[0:15]
	s_waitcnt lgkmcnt(0)
	v_mfma_f32_32x32x16_bf16 v[16:31], v[204:207], v[76:79], v[16:31]
	s_setprio 0
.LBB0_597:
	s_andn2_b64 vcc, exec, s[50:51]
	s_cbranch_vccnz .LBB0_579
	s_branch .LBB0_578

.LBB0_606:
	s_or_b64 exec, exec, s[10:11]
	v_and_b32_e32 v237, 16, v191
	v_lshlrev_b32_e32 v237, 2, v237
	v_xor_b32_e32 v234, v237, v180
	v_mov_b32_e32 v235, v181
	global_load_dwordx4 v[112:115], v[234:235], off offset:1024
	s_waitcnt vmcnt(1)
	ds_write_b128 v119, v[104:107]
	s_and_saveexec_b64 s[10:11], s[4:5]
	ds_write_b128 v119, v[108:111] offset:8192
	s_or_b64 exec, exec, s[10:11]
	s_sub_i32 s10, 0x1000, s62
	s_ashr_i32 s50, s10, 6
	s_cmp_lt_i32 s50, 1
	s_waitcnt vmcnt(0)
	ds_write_b128 v119, v[112:115] offset:24576
	s_waitcnt lgkmcnt(0)
	s_barrier
	s_cbranch_scc1 .LBB0_633
	v_mov_b32_e32 v14, v121
	v_mov_b32_e32 v15, v121
	v_mov_b32_e32 v0, v121
	v_mov_b32_e32 v1, v121
	v_mov_b32_e32 v2, v121
	v_mov_b32_e32 v3, v121
	v_mov_b32_e32 v4, v121
	v_mov_b32_e32 v5, v121
	v_mov_b32_e32 v6, v121
	v_mov_b32_e32 v7, v121
	v_mov_b32_e32 v8, v121
	v_mov_b32_e32 v9, v121
	v_mov_b32_e32 v10, v121
	v_mov_b32_e32 v11, v121
	v_mov_b32_e32 v12, v121
	v_mov_b32_e32 v13, v121
	v_mov_b32_e32 v143, 0
	v_mov_b64_e32 v[30:31], v[14:15]
	s_or_b32 s51, s47, 31
	s_sub_i32 s62, 0, s50
	s_mov_b32 s63, 1
	s_mov_b32 s64, 63
	v_mov_b64_e32 v[28:29], v[12:13]
	v_mov_b64_e32 v[26:27], v[10:11]
	v_mov_b64_e32 v[24:25], v[8:9]
	v_mov_b64_e32 v[22:23], v[6:7]
	v_mov_b64_e32 v[20:21], v[4:5]
	v_mov_b64_e32 v[18:19], v[2:3]
	v_mov_b64_e32 v[16:17], v[0:1]
	v_mov_b32_e32 v141, 0
	v_mov_b32_e32 v32, 0
	v_mov_b32_e32 v33, v143
	v_mov_b32_e32 v34, v143
	v_mov_b32_e32 v35, v143
	v_mov_b32_e32 v36, v143
	v_mov_b32_e32 v37, v143
	v_mov_b32_e32 v38, v143
	v_mov_b32_e32 v39, v143
	v_mov_b32_e32 v40, v143
	v_mov_b32_e32 v41, v143
	v_mov_b32_e32 v42, v143
	v_mov_b32_e32 v43, v143
	v_mov_b32_e32 v44, v143
	v_mov_b32_e32 v45, v143
	v_mov_b32_e32 v46, v143
	v_mov_b32_e32 v47, v143
	v_bfe_u32 v232, v191, 2, 2
	v_bfe_u32 v233, v191, 5, 1
	v_lshl_add_u32 v233, v233, 2, v232
	v_lshlrev_b32_e32 v238, 7, v233
	v_bfe_u32 v233, v191, 4, 1
	v_bfe_u32 v234, v191, 1, 1
	v_lshl_or_b32 v233, v233, 1, v234
	v_lshrrev_b32_e32 v232, 1, v232
	v_lshlrev_b32_e32 v232, 2, v232
	v_xor_b32_e32 v233, v233, v232
	v_lshl_add_u32 v238, v233, 4, v238
	v_and_b32_e32 v232, 1, v191
	v_lshl_add_u32 v238, v232, 3, v238
	v_xor_b32_e32 v239, 64, v238
	v_readfirstlane_b32 s99, v119
	v_xor_b32_e32 v170, v237, v170
	s_branch .LBB0_612
.LBB0_610:
	s_waitcnt vmcnt(0)
.LBB0_611:
	s_add_i32 s63, s63, 1
	s_add_i32 s64, s64, 64
	s_add_i32 s10, s62, s63
	v_lshl_add_u64 v[170:171], v[170:171], 0, s[40:41]
	v_lshl_add_u64 v[172:173], v[172:173], 0, s[42:43]
	s_cmp_eq_u32 s10, 1
	v_lshl_add_u64 v[174:175], v[174:175], 0, s[40:41]
	s_waitcnt lgkmcnt(0)
	s_barrier
	s_cbranch_scc1 .LBB0_634
.LBB0_612:
	s_cmp_lt_i32 s63, s50
	s_cselect_b64 s[48:49], -1, 0
	s_cmp_ge_i32 s63, s50
	s_cbranch_scc1 .LBB0_616
	s_and_b32 s10, s63, 1
	s_mul_i32 s11, s10, 0x3000
	s_add_i32 s11, s11, s99
	s_mov_b32 m0, s11
	s_nop 0
	global_load_lds_dwordx4 v[174:175], off
	s_cmp_lg_u64 s[4:5], 0
	s_cbranch_scc0 .LBB0_615
	s_add_i32 m0, s11, 0x2000
	s_nop 0
	global_load_lds_dwordx4 v[172:173], off
.LBB0_615:
	s_mulk_i32 s10, 0x2200
	s_add_i32 s10, s10, s99
	s_add_i32 m0, s10, 0x6000
	s_nop 0
	global_load_lds_dwordx4 v[170:171], off

.LBB0_629:
	s_andn2_b64 vcc, exec, s[48:49]
	s_cbranch_vccnz .LBB0_611
	s_branch .LBB0_610
